# adds: gMLP prompt item: the GV row-pair loads of a group iteration issued together at its top
# baseline (speedup 1.0000x reference)
.LBB0_453:
	v_lshl_add_u64 v[4:5], s[12:13], 0, v[32:33]
	v_add_co_u32_e32 v18, vcc, 0x696e000, v4
	s_add_u32 s0, s16, s70
	s_nop 0
	v_addc_co_u32_e32 v19, vcc, 0, v5, vcc
	global_load_dwordx4 v[190:193], v[18:19], off
	global_load_dwordx4 v[194:197], v[18:19], off offset:2048
	global_load_dwordx4 v[198:201], v[18:19], off offset:16
	global_load_dwordx4 v[202:205], v[18:19], off offset:2064
	global_load_dwordx4 v[206:209], v[18:19], off offset:32
	global_load_dwordx4 v[210:213], v[18:19], off offset:2080
	global_load_dwordx4 v[214:217], v[18:19], off offset:48
	global_load_dwordx4 v[218:221], v[18:19], off offset:2096
	s_addc_u32 s1, s38, s71
	s_add_u32 s4, s88, s70
	s_addc_u32 s5, s89, s71
	global_load_dwordx2 v[20:21], v2, s[0:1]
	global_load_dwordx2 v[22:23], v2, s[4:5]
	v_mov_b64_e32 v[16:17], s[44:45]
	ds_read_b64 v[14:15], v68
	ds_read_b64 v[12:13], v69
	s_waitcnt vmcnt(9)
	v_lshlrev_b32_e32 v24, 16, v190
	v_and_b32_e32 v25, 0xffff0000, v190
	s_waitcnt vmcnt(8)
	v_lshlrev_b32_e32 v34, 16, v194
	v_and_b32_e32 v35, 0xffff0000, v194
	v_and_b32_e32 v37, 0x7fffffff, v25
	v_and_b32_e32 v36, 0x7fffffff, v24
	v_and_b32_e32 v41, 0x7fffffff, v35
	v_and_b32_e32 v40, 0x7fffffff, v34
	v_pk_fma_f32 v[36:37], v[36:37], s[40:41], 1.0 op_sel_hi:[1,0,0]
	v_pk_fma_f32 v[40:41], v[40:41], s[40:41], 1.0 op_sel_hi:[1,0,0]
	v_rcp_f32_e32 v36, v36
	v_rcp_f32_e32 v37, v37
	v_rcp_f32_e32 v40, v40
	v_rcp_f32_e32 v41, v41
	v_pk_mul_f32 v[38:39], v[24:25], v[24:25]
	v_pk_mul_f32 v[42:43], v[34:35], v[34:35]
	v_pk_mul_f32 v[38:39], v[38:39], s[64:65] op_sel_hi:[1,0]
	v_pk_fma_f32 v[44:45], v[36:37], s[42:43], v[16:17] op_sel_hi:[1,0,0]
	v_pk_mul_f32 v[42:43], v[42:43], s[64:65] op_sel_hi:[1,0]
	v_exp_f32_e32 v38, v38
	v_exp_f32_e32 v39, v39
	v_pk_fma_f32 v[46:47], v[40:41], s[42:43], v[16:17] op_sel_hi:[1,0,0]
	v_pk_fma_f32 v[44:45], v[36:37], v[44:45], s[48:49] op_sel_hi:[1,1,0]
	v_exp_f32_e32 v42, v42
	v_exp_f32_e32 v43, v43
	v_pk_fma_f32 v[46:47], v[40:41], v[46:47], s[48:49] op_sel_hi:[1,1,0]
	v_pk_fma_f32 v[44:45], v[36:37], v[44:45], s[50:51] op_sel_hi:[1,1,0]
	v_pk_fma_f32 v[46:47], v[40:41], v[46:47], s[50:51] op_sel_hi:[1,1,0]
	v_pk_fma_f32 v[44:45], v[36:37], v[44:45], s[56:57] op_sel_hi:[1,1,0]
	v_pk_fma_f32 v[46:47], v[40:41], v[46:47], s[56:57] op_sel_hi:[1,1,0]
	v_pk_mul_f32 v[36:37], v[36:37], v[44:45]
	v_pk_mul_f32 v[40:41], v[40:41], v[46:47]
	v_pk_mul_f32 v[36:37], v[38:39], v[36:37]
	v_pk_mul_f32 v[38:39], v[42:43], v[40:41]
	v_pk_mul_f32 v[40:41], v[24:25], v[36:37]
	v_pk_fma_f32 v[36:37], v[24:25], v[36:37], v[24:25] neg_lo:[1,0,0] neg_hi:[1,0,0]
	v_cmp_gt_f32_e32 vcc, 0, v24
	v_pk_mul_f32 v[42:43], v[34:35], v[38:39]
	v_pk_fma_f32 v[38:39], v[34:35], v[38:39], v[34:35] neg_lo:[1,0,0] neg_hi:[1,0,0]
	v_cndmask_b32_e32 v3, v36, v40, vcc
	v_cmp_gt_f32_e32 vcc, 0, v25
	s_waitcnt lgkmcnt(1)
	v_sub_f32_e32 v3, v3, v14
	s_waitcnt lgkmcnt(0)
	v_mul_f32_e32 v3, v12, v3
	v_cndmask_b32_e32 v4, v37, v41, vcc
	v_cmp_gt_f32_e32 vcc, 0, v34
	v_sub_f32_e32 v4, v4, v14
	v_mul_f32_e32 v4, v12, v4
	v_cndmask_b32_e32 v8, v38, v42, vcc
	v_cmp_gt_f32_e32 vcc, 0, v35
	v_sub_f32_e32 v8, v8, v15
	v_mul_f32_e32 v8, v13, v8
	v_cndmask_b32_e32 v24, v39, v43, vcc
	v_sub_f32_e32 v24, v24, v15
	v_mul_f32_e32 v24, v13, v24
	s_waitcnt vmcnt(0)
	v_fma_f32 v3, v20, v3, v22
	v_fma_f32 v4, v21, v4, v23
	v_fma_f32 v8, v20, v8, v22
	v_fmac_f32_e32 v23, v21, v24
	v_cvt_pk_bf16_f32 v3, v3, v8
	ds_write_b32 v70, v3
	v_cvt_pk_bf16_f32 v3, v4, v23
	global_load_dwordx2 v[22:23], v2, s[0:1] offset:8
	global_load_dwordx2 v[20:21], v2, s[4:5] offset:8
	v_lshlrev_b32_e32 v8, 16, v191
	v_and_b32_e32 v9, 0xffff0000, v191
	v_lshlrev_b32_e32 v4, 16, v195
	v_and_b32_e32 v5, 0xffff0000, v195
	v_and_b32_e32 v25, 0x7fffffff, v9
	v_and_b32_e32 v24, 0x7fffffff, v8
	v_and_b32_e32 v37, 0x7fffffff, v5
	v_and_b32_e32 v36, 0x7fffffff, v4
	v_pk_fma_f32 v[24:25], v[24:25], s[40:41], 1.0 op_sel_hi:[1,0,0]
	v_pk_fma_f32 v[36:37], v[36:37], s[40:41], 1.0 op_sel_hi:[1,0,0]
	v_rcp_f32_e32 v24, v24
	v_rcp_f32_e32 v25, v25
	v_rcp_f32_e32 v36, v36
	v_rcp_f32_e32 v37, v37
	v_pk_mul_f32 v[34:35], v[8:9], v[8:9]
	v_pk_mul_f32 v[38:39], v[4:5], v[4:5]
	v_pk_mul_f32 v[34:35], v[34:35], s[64:65] op_sel_hi:[1,0]
	v_pk_fma_f32 v[40:41], v[24:25], s[42:43], v[16:17] op_sel_hi:[1,0,0]
	v_pk_mul_f32 v[38:39], v[38:39], s[64:65] op_sel_hi:[1,0]
	v_exp_f32_e32 v34, v34
	v_exp_f32_e32 v35, v35
	v_pk_fma_f32 v[42:43], v[36:37], s[42:43], v[16:17] op_sel_hi:[1,0,0]
	v_pk_fma_f32 v[40:41], v[24:25], v[40:41], s[48:49] op_sel_hi:[1,1,0]
	v_exp_f32_e32 v38, v38
	v_exp_f32_e32 v39, v39
	v_pk_fma_f32 v[42:43], v[36:37], v[42:43], s[48:49] op_sel_hi:[1,1,0]
	v_pk_fma_f32 v[40:41], v[24:25], v[40:41], s[50:51] op_sel_hi:[1,1,0]
	v_pk_fma_f32 v[42:43], v[36:37], v[42:43], s[50:51] op_sel_hi:[1,1,0]
	v_pk_fma_f32 v[40:41], v[24:25], v[40:41], s[56:57] op_sel_hi:[1,1,0]
	v_pk_fma_f32 v[42:43], v[36:37], v[42:43], s[56:57] op_sel_hi:[1,1,0]
	v_pk_mul_f32 v[24:25], v[24:25], v[40:41]
	v_pk_mul_f32 v[36:37], v[36:37], v[42:43]
	v_pk_mul_f32 v[24:25], v[34:35], v[24:25]
	v_pk_mul_f32 v[34:35], v[38:39], v[36:37]
	v_pk_mul_f32 v[36:37], v[8:9], v[24:25]
	v_pk_fma_f32 v[24:25], v[8:9], v[24:25], v[8:9] neg_lo:[1,0,0] neg_hi:[1,0,0]
	v_cmp_gt_f32_e32 vcc, 0, v8
	v_pk_mul_f32 v[38:39], v[4:5], v[34:35]
	v_pk_fma_f32 v[34:35], v[4:5], v[34:35], v[4:5] neg_lo:[1,0,0] neg_hi:[1,0,0]
	v_cndmask_b32_e32 v8, v24, v36, vcc
	v_cmp_gt_f32_e32 vcc, 0, v9
	v_sub_f32_e32 v8, v8, v14
	v_mul_f32_e32 v8, v12, v8
	v_cndmask_b32_e32 v9, v25, v37, vcc
	v_cmp_gt_f32_e32 vcc, 0, v4
	v_sub_f32_e32 v9, v9, v14
	v_mul_f32_e32 v9, v12, v9
	v_cndmask_b32_e32 v4, v34, v38, vcc
	v_cmp_gt_f32_e32 vcc, 0, v5
	v_sub_f32_e32 v4, v4, v15
	v_mul_f32_e32 v4, v13, v4
	v_cndmask_b32_e32 v5, v35, v39, vcc
	v_sub_f32_e32 v5, v5, v15
	ds_write_b32 v70, v3 offset:272
	v_mul_f32_e32 v5, v13, v5
	s_waitcnt vmcnt(0)
	v_fma_f32 v3, v22, v8, v20
	v_fma_f32 v8, v23, v9, v21
	v_fma_f32 v4, v22, v4, v20
	v_cvt_pk_bf16_f32 v3, v3, v4
	v_fmac_f32_e32 v21, v23, v5
	ds_write_b32 v70, v3 offset:544
	v_cvt_pk_bf16_f32 v3, v8, v21
	global_load_dwordx2 v[8:9], v2, s[0:1] offset:16
	global_load_dwordx2 v[4:5], v2, s[4:5] offset:16
	v_lshlrev_b32_e32 v20, 16, v192
	v_and_b32_e32 v21, 0xffff0000, v192
	v_lshlrev_b32_e32 v22, 16, v196
	v_and_b32_e32 v23, 0xffff0000, v196
	v_and_b32_e32 v25, 0x7fffffff, v21
	v_and_b32_e32 v24, 0x7fffffff, v20
	v_and_b32_e32 v37, 0x7fffffff, v23
	v_and_b32_e32 v36, 0x7fffffff, v22
	v_pk_fma_f32 v[24:25], v[24:25], s[40:41], 1.0 op_sel_hi:[1,0,0]
	v_pk_fma_f32 v[36:37], v[36:37], s[40:41], 1.0 op_sel_hi:[1,0,0]
	v_rcp_f32_e32 v24, v24
	v_rcp_f32_e32 v25, v25
	v_rcp_f32_e32 v36, v36
	v_rcp_f32_e32 v37, v37
	v_pk_mul_f32 v[34:35], v[20:21], v[20:21]
	v_pk_mul_f32 v[38:39], v[22:23], v[22:23]
	v_pk_mul_f32 v[34:35], v[34:35], s[64:65] op_sel_hi:[1,0]
	v_pk_fma_f32 v[40:41], v[24:25], s[42:43], v[16:17] op_sel_hi:[1,0,0]
	v_pk_mul_f32 v[38:39], v[38:39], s[64:65] op_sel_hi:[1,0]
	v_exp_f32_e32 v34, v34
	v_exp_f32_e32 v35, v35
	v_pk_fma_f32 v[42:43], v[36:37], s[42:43], v[16:17] op_sel_hi:[1,0,0]
	v_pk_fma_f32 v[40:41], v[24:25], v[40:41], s[48:49] op_sel_hi:[1,1,0]
	v_exp_f32_e32 v38, v38
	v_exp_f32_e32 v39, v39
	v_pk_fma_f32 v[42:43], v[36:37], v[42:43], s[48:49] op_sel_hi:[1,1,0]
	v_pk_fma_f32 v[40:41], v[24:25], v[40:41], s[50:51] op_sel_hi:[1,1,0]
	v_pk_fma_f32 v[42:43], v[36:37], v[42:43], s[50:51] op_sel_hi:[1,1,0]
	v_pk_fma_f32 v[40:41], v[24:25], v[40:41], s[56:57] op_sel_hi:[1,1,0]
	v_pk_fma_f32 v[42:43], v[36:37], v[42:43], s[56:57] op_sel_hi:[1,1,0]
	v_pk_mul_f32 v[24:25], v[24:25], v[40:41]
	v_pk_mul_f32 v[36:37], v[36:37], v[42:43]
	v_pk_mul_f32 v[24:25], v[34:35], v[24:25]
	v_pk_mul_f32 v[34:35], v[38:39], v[36:37]
	v_pk_mul_f32 v[36:37], v[20:21], v[24:25]
	v_pk_fma_f32 v[24:25], v[20:21], v[24:25], v[20:21] neg_lo:[1,0,0] neg_hi:[1,0,0]
	v_cmp_gt_f32_e32 vcc, 0, v20
	v_pk_mul_f32 v[38:39], v[22:23], v[34:35]
	v_pk_fma_f32 v[34:35], v[22:23], v[34:35], v[22:23] neg_lo:[1,0,0] neg_hi:[1,0,0]
	v_cndmask_b32_e32 v6, v24, v36, vcc
	v_cmp_gt_f32_e32 vcc, 0, v21
	v_sub_f32_e32 v6, v6, v14
	v_mul_f32_e32 v6, v12, v6
	v_cndmask_b32_e32 v10, v25, v37, vcc
	v_cmp_gt_f32_e32 vcc, 0, v22
	v_sub_f32_e32 v10, v10, v14
	v_mul_f32_e32 v10, v12, v10
	v_cndmask_b32_e32 v20, v34, v38, vcc
	v_cmp_gt_f32_e32 vcc, 0, v23
	v_sub_f32_e32 v20, v20, v15
	v_mul_f32_e32 v20, v13, v20
	v_cndmask_b32_e32 v21, v35, v39, vcc
	v_sub_f32_e32 v21, v21, v15
	v_mul_f32_e32 v21, v13, v21
	ds_write_b32 v70, v3 offset:816
	s_waitcnt vmcnt(0)
	v_fma_f32 v3, v8, v6, v4
	v_fma_f32 v6, v9, v10, v5
	v_fma_f32 v4, v8, v20, v4
	v_fmac_f32_e32 v5, v9, v21
	v_cvt_pk_bf16_f32 v3, v3, v4
	ds_write_b32 v70, v3 offset:1088
	v_cvt_pk_bf16_f32 v3, v6, v5
	global_load_dwordx2 v[8:9], v2, s[0:1] offset:24
	global_load_dwordx2 v[4:5], v2, s[4:5] offset:24
	v_lshlrev_b32_e32 v10, 16, v193
	v_and_b32_e32 v11, 0xffff0000, v193
	v_lshlrev_b32_e32 v6, 16, v197
	v_and_b32_e32 v7, 0xffff0000, v197
	v_and_b32_e32 v21, 0x7fffffff, v11
	v_and_b32_e32 v20, 0x7fffffff, v10
	v_and_b32_e32 v25, 0x7fffffff, v7
	v_and_b32_e32 v24, 0x7fffffff, v6
	v_pk_fma_f32 v[20:21], v[20:21], s[40:41], 1.0 op_sel_hi:[1,0,0]
	v_pk_fma_f32 v[24:25], v[24:25], s[40:41], 1.0 op_sel_hi:[1,0,0]
	v_rcp_f32_e32 v20, v20
	v_rcp_f32_e32 v21, v21
	v_rcp_f32_e32 v24, v24
	v_rcp_f32_e32 v25, v25
	v_pk_mul_f32 v[22:23], v[10:11], v[10:11]
	v_pk_mul_f32 v[34:35], v[6:7], v[6:7]
	v_pk_mul_f32 v[22:23], v[22:23], s[64:65] op_sel_hi:[1,0]
	v_pk_fma_f32 v[36:37], v[20:21], s[42:43], v[16:17] op_sel_hi:[1,0,0]
	v_pk_mul_f32 v[34:35], v[34:35], s[64:65] op_sel_hi:[1,0]
	v_exp_f32_e32 v22, v22
	v_exp_f32_e32 v23, v23
	v_pk_fma_f32 v[38:39], v[24:25], s[42:43], v[16:17] op_sel_hi:[1,0,0]
	v_pk_fma_f32 v[36:37], v[20:21], v[36:37], s[48:49] op_sel_hi:[1,1,0]
	v_exp_f32_e32 v34, v34
	v_exp_f32_e32 v35, v35
	v_pk_fma_f32 v[38:39], v[24:25], v[38:39], s[48:49] op_sel_hi:[1,1,0]
	v_pk_fma_f32 v[36:37], v[20:21], v[36:37], s[50:51] op_sel_hi:[1,1,0]
	v_pk_fma_f32 v[38:39], v[24:25], v[38:39], s[50:51] op_sel_hi:[1,1,0]
	v_pk_fma_f32 v[36:37], v[20:21], v[36:37], s[56:57] op_sel_hi:[1,1,0]
	v_pk_fma_f32 v[38:39], v[24:25], v[38:39], s[56:57] op_sel_hi:[1,1,0]
	v_pk_mul_f32 v[20:21], v[20:21], v[36:37]
	v_pk_mul_f32 v[24:25], v[24:25], v[38:39]
	v_pk_mul_f32 v[20:21], v[22:23], v[20:21]
	v_pk_mul_f32 v[22:23], v[34:35], v[24:25]
	v_pk_mul_f32 v[24:25], v[10:11], v[20:21]
	v_pk_fma_f32 v[20:21], v[10:11], v[20:21], v[10:11] neg_lo:[1,0,0] neg_hi:[1,0,0]
	v_cmp_gt_f32_e32 vcc, 0, v10
	v_pk_mul_f32 v[34:35], v[6:7], v[22:23]
	v_pk_fma_f32 v[22:23], v[6:7], v[22:23], v[6:7] neg_lo:[1,0,0] neg_hi:[1,0,0]
	v_cndmask_b32_e32 v10, v20, v24, vcc
	v_cmp_gt_f32_e32 vcc, 0, v11
	v_sub_f32_e32 v10, v10, v14
	v_mul_f32_e32 v10, v12, v10
	v_cndmask_b32_e32 v11, v21, v25, vcc
	v_cmp_gt_f32_e32 vcc, 0, v6
	v_sub_f32_e32 v11, v11, v14
	v_mul_f32_e32 v11, v12, v11
	v_cndmask_b32_e32 v6, v22, v34, vcc
	v_cmp_gt_f32_e32 vcc, 0, v7
	v_sub_f32_e32 v6, v6, v15
	v_mul_f32_e32 v6, v13, v6
	v_cndmask_b32_e32 v7, v23, v35, vcc
	v_sub_f32_e32 v7, v7, v15
	v_mul_f32_e32 v7, v13, v7
	ds_write_b32 v70, v3 offset:1360
	s_waitcnt vmcnt(0)
	v_fma_f32 v3, v8, v10, v4
	v_fma_f32 v10, v9, v11, v5
	v_fma_f32 v4, v8, v6, v4
	v_fmac_f32_e32 v5, v9, v7
	v_cvt_pk_bf16_f32 v3, v3, v4
	ds_write_b32 v70, v3 offset:1632
	v_cvt_pk_bf16_f32 v3, v10, v5
	global_load_dwordx2 v[22:23], v2, s[0:1] offset:32
	global_load_dwordx2 v[20:21], v2, s[4:5] offset:32
	ds_write_b32 v70, v3 offset:1904
	s_waitcnt vmcnt(3)
	v_lshlrev_b32_e32 v24, 16, v198
	v_and_b32_e32 v25, 0xffff0000, v198
	s_waitcnt vmcnt(2)
	v_lshlrev_b32_e32 v34, 16, v202
	v_and_b32_e32 v35, 0xffff0000, v202
	v_and_b32_e32 v37, 0x7fffffff, v25
	v_and_b32_e32 v36, 0x7fffffff, v24
	v_and_b32_e32 v41, 0x7fffffff, v35
	v_and_b32_e32 v40, 0x7fffffff, v34
	v_pk_fma_f32 v[36:37], v[36:37], s[40:41], 1.0 op_sel_hi:[1,0,0]
	v_pk_fma_f32 v[40:41], v[40:41], s[40:41], 1.0 op_sel_hi:[1,0,0]
	v_rcp_f32_e32 v36, v36
	v_rcp_f32_e32 v37, v37
	v_rcp_f32_e32 v40, v40
	v_rcp_f32_e32 v41, v41
	v_pk_mul_f32 v[38:39], v[24:25], v[24:25]
	v_pk_mul_f32 v[42:43], v[34:35], v[34:35]
	v_pk_mul_f32 v[38:39], v[38:39], s[64:65] op_sel_hi:[1,0]
	v_pk_fma_f32 v[44:45], v[36:37], s[42:43], v[16:17] op_sel_hi:[1,0,0]
	v_pk_mul_f32 v[42:43], v[42:43], s[64:65] op_sel_hi:[1,0]
	v_exp_f32_e32 v38, v38
	v_exp_f32_e32 v39, v39
	v_pk_fma_f32 v[46:47], v[40:41], s[42:43], v[16:17] op_sel_hi:[1,0,0]
	v_pk_fma_f32 v[44:45], v[36:37], v[44:45], s[48:49] op_sel_hi:[1,1,0]
	v_exp_f32_e32 v42, v42
	v_exp_f32_e32 v43, v43
	v_pk_fma_f32 v[46:47], v[40:41], v[46:47], s[48:49] op_sel_hi:[1,1,0]
	v_pk_fma_f32 v[44:45], v[36:37], v[44:45], s[50:51] op_sel_hi:[1,1,0]
	v_pk_fma_f32 v[46:47], v[40:41], v[46:47], s[50:51] op_sel_hi:[1,1,0]
	v_pk_fma_f32 v[44:45], v[36:37], v[44:45], s[56:57] op_sel_hi:[1,1,0]
	v_pk_fma_f32 v[46:47], v[40:41], v[46:47], s[56:57] op_sel_hi:[1,1,0]
	v_pk_mul_f32 v[36:37], v[36:37], v[44:45]
	v_pk_mul_f32 v[40:41], v[40:41], v[46:47]
	v_pk_mul_f32 v[36:37], v[38:39], v[36:37]
	v_pk_mul_f32 v[38:39], v[42:43], v[40:41]
	v_pk_mul_f32 v[40:41], v[24:25], v[36:37]
	v_pk_fma_f32 v[36:37], v[24:25], v[36:37], v[24:25] neg_lo:[1,0,0] neg_hi:[1,0,0]
	v_cmp_gt_f32_e32 vcc, 0, v24
	v_pk_mul_f32 v[42:43], v[34:35], v[38:39]
	v_pk_fma_f32 v[38:39], v[34:35], v[38:39], v[34:35] neg_lo:[1,0,0] neg_hi:[1,0,0]
	v_cndmask_b32_e32 v3, v36, v40, vcc
	v_cmp_gt_f32_e32 vcc, 0, v25
	v_sub_f32_e32 v3, v3, v14
	v_mul_f32_e32 v3, v12, v3
	v_cndmask_b32_e32 v4, v37, v41, vcc
	v_cmp_gt_f32_e32 vcc, 0, v34
	v_sub_f32_e32 v4, v4, v14
	v_mul_f32_e32 v4, v12, v4
	v_cndmask_b32_e32 v8, v38, v42, vcc
	v_cmp_gt_f32_e32 vcc, 0, v35
	v_sub_f32_e32 v8, v8, v15
	v_mul_f32_e32 v8, v13, v8
	v_cndmask_b32_e32 v24, v39, v43, vcc
	v_sub_f32_e32 v24, v24, v15
	v_mul_f32_e32 v24, v13, v24
	s_waitcnt vmcnt(0)
	v_fma_f32 v3, v22, v3, v20
	v_fma_f32 v4, v23, v4, v21
	v_fma_f32 v8, v22, v8, v20
	v_fmac_f32_e32 v21, v23, v24
	v_cvt_pk_bf16_f32 v3, v3, v8
	ds_write_b32 v70, v3 offset:2176
	v_cvt_pk_bf16_f32 v3, v4, v21
	global_load_dwordx2 v[22:23], v2, s[0:1] offset:40
	global_load_dwordx2 v[20:21], v2, s[4:5] offset:40
	v_lshlrev_b32_e32 v8, 16, v199
	v_and_b32_e32 v9, 0xffff0000, v199
	v_lshlrev_b32_e32 v4, 16, v203
	v_and_b32_e32 v5, 0xffff0000, v203
	v_and_b32_e32 v25, 0x7fffffff, v9
	v_and_b32_e32 v24, 0x7fffffff, v8
	v_and_b32_e32 v37, 0x7fffffff, v5
	v_and_b32_e32 v36, 0x7fffffff, v4
	v_pk_fma_f32 v[24:25], v[24:25], s[40:41], 1.0 op_sel_hi:[1,0,0]
	v_pk_fma_f32 v[36:37], v[36:37], s[40:41], 1.0 op_sel_hi:[1,0,0]
	v_rcp_f32_e32 v24, v24
	v_rcp_f32_e32 v25, v25
	v_rcp_f32_e32 v36, v36
	v_rcp_f32_e32 v37, v37
	v_pk_mul_f32 v[34:35], v[8:9], v[8:9]
	v_pk_mul_f32 v[38:39], v[4:5], v[4:5]
	v_pk_mul_f32 v[34:35], v[34:35], s[64:65] op_sel_hi:[1,0]
	v_pk_fma_f32 v[40:41], v[24:25], s[42:43], v[16:17] op_sel_hi:[1,0,0]
	v_pk_mul_f32 v[38:39], v[38:39], s[64:65] op_sel_hi:[1,0]
	v_exp_f32_e32 v34, v34
	v_exp_f32_e32 v35, v35
	v_pk_fma_f32 v[42:43], v[36:37], s[42:43], v[16:17] op_sel_hi:[1,0,0]
	v_pk_fma_f32 v[40:41], v[24:25], v[40:41], s[48:49] op_sel_hi:[1,1,0]
	v_exp_f32_e32 v38, v38
	v_exp_f32_e32 v39, v39
	v_pk_fma_f32 v[42:43], v[36:37], v[42:43], s[48:49] op_sel_hi:[1,1,0]
	v_pk_fma_f32 v[40:41], v[24:25], v[40:41], s[50:51] op_sel_hi:[1,1,0]
	v_pk_fma_f32 v[42:43], v[36:37], v[42:43], s[50:51] op_sel_hi:[1,1,0]
	v_pk_fma_f32 v[40:41], v[24:25], v[40:41], s[56:57] op_sel_hi:[1,1,0]
	v_pk_fma_f32 v[42:43], v[36:37], v[42:43], s[56:57] op_sel_hi:[1,1,0]
	v_pk_mul_f32 v[24:25], v[24:25], v[40:41]
	v_pk_mul_f32 v[36:37], v[36:37], v[42:43]
	v_pk_mul_f32 v[24:25], v[34:35], v[24:25]
	v_pk_mul_f32 v[34:35], v[38:39], v[36:37]
	v_pk_mul_f32 v[36:37], v[8:9], v[24:25]
	v_pk_fma_f32 v[24:25], v[8:9], v[24:25], v[8:9] neg_lo:[1,0,0] neg_hi:[1,0,0]
	v_cmp_gt_f32_e32 vcc, 0, v8
	v_pk_mul_f32 v[38:39], v[4:5], v[34:35]
	v_pk_fma_f32 v[34:35], v[4:5], v[34:35], v[4:5] neg_lo:[1,0,0] neg_hi:[1,0,0]
	v_cndmask_b32_e32 v8, v24, v36, vcc
	v_cmp_gt_f32_e32 vcc, 0, v9
	v_sub_f32_e32 v8, v8, v14
	v_mul_f32_e32 v8, v12, v8
	v_cndmask_b32_e32 v9, v25, v37, vcc
	v_cmp_gt_f32_e32 vcc, 0, v4
	v_sub_f32_e32 v9, v9, v14
	v_mul_f32_e32 v9, v12, v9
	v_cndmask_b32_e32 v4, v34, v38, vcc
	v_cmp_gt_f32_e32 vcc, 0, v5
	v_sub_f32_e32 v4, v4, v15
	v_mul_f32_e32 v4, v13, v4
	v_cndmask_b32_e32 v5, v35, v39, vcc
	v_sub_f32_e32 v5, v5, v15
	ds_write_b32 v70, v3 offset:2448
	v_mul_f32_e32 v5, v13, v5
	s_waitcnt vmcnt(0)
	v_fma_f32 v3, v22, v8, v20
	v_fma_f32 v8, v23, v9, v21
	v_fma_f32 v4, v22, v4, v20
	v_cvt_pk_bf16_f32 v3, v3, v4
	v_fmac_f32_e32 v21, v23, v5
	ds_write_b32 v70, v3 offset:2720
	v_cvt_pk_bf16_f32 v3, v8, v21
	global_load_dwordx2 v[8:9], v2, s[0:1] offset:48
	global_load_dwordx2 v[4:5], v2, s[4:5] offset:48
	v_lshlrev_b32_e32 v20, 16, v200
	v_and_b32_e32 v21, 0xffff0000, v200
	v_lshlrev_b32_e32 v22, 16, v204
	v_and_b32_e32 v23, 0xffff0000, v204
	v_and_b32_e32 v25, 0x7fffffff, v21
	v_and_b32_e32 v24, 0x7fffffff, v20
	v_and_b32_e32 v37, 0x7fffffff, v23
	v_and_b32_e32 v36, 0x7fffffff, v22
	v_pk_fma_f32 v[24:25], v[24:25], s[40:41], 1.0 op_sel_hi:[1,0,0]
	v_pk_fma_f32 v[36:37], v[36:37], s[40:41], 1.0 op_sel_hi:[1,0,0]
	v_rcp_f32_e32 v24, v24
	v_rcp_f32_e32 v25, v25
	v_rcp_f32_e32 v36, v36
	v_rcp_f32_e32 v37, v37
	v_pk_mul_f32 v[34:35], v[20:21], v[20:21]
	v_pk_mul_f32 v[38:39], v[22:23], v[22:23]
	v_pk_mul_f32 v[34:35], v[34:35], s[64:65] op_sel_hi:[1,0]
	v_pk_fma_f32 v[40:41], v[24:25], s[42:43], v[16:17] op_sel_hi:[1,0,0]
	v_pk_mul_f32 v[38:39], v[38:39], s[64:65] op_sel_hi:[1,0]
	v_exp_f32_e32 v34, v34
	v_exp_f32_e32 v35, v35
	v_pk_fma_f32 v[42:43], v[36:37], s[42:43], v[16:17] op_sel_hi:[1,0,0]
	v_pk_fma_f32 v[40:41], v[24:25], v[40:41], s[48:49] op_sel_hi:[1,1,0]
	v_exp_f32_e32 v38, v38
	v_exp_f32_e32 v39, v39
	v_pk_fma_f32 v[42:43], v[36:37], v[42:43], s[48:49] op_sel_hi:[1,1,0]
	v_pk_fma_f32 v[40:41], v[24:25], v[40:41], s[50:51] op_sel_hi:[1,1,0]
	v_pk_fma_f32 v[42:43], v[36:37], v[42:43], s[50:51] op_sel_hi:[1,1,0]
	v_pk_fma_f32 v[40:41], v[24:25], v[40:41], s[56:57] op_sel_hi:[1,1,0]
	v_pk_fma_f32 v[42:43], v[36:37], v[42:43], s[56:57] op_sel_hi:[1,1,0]
	v_pk_mul_f32 v[24:25], v[24:25], v[40:41]
	v_pk_mul_f32 v[36:37], v[36:37], v[42:43]
	v_pk_mul_f32 v[24:25], v[34:35], v[24:25]
	v_pk_mul_f32 v[34:35], v[38:39], v[36:37]
	v_pk_mul_f32 v[36:37], v[20:21], v[24:25]
	v_pk_fma_f32 v[24:25], v[20:21], v[24:25], v[20:21] neg_lo:[1,0,0] neg_hi:[1,0,0]
	v_cmp_gt_f32_e32 vcc, 0, v20
	v_pk_mul_f32 v[38:39], v[22:23], v[34:35]
	v_pk_fma_f32 v[34:35], v[22:23], v[34:35], v[22:23] neg_lo:[1,0,0] neg_hi:[1,0,0]
	v_cndmask_b32_e32 v6, v24, v36, vcc
	v_cmp_gt_f32_e32 vcc, 0, v21
	v_sub_f32_e32 v6, v6, v14
	v_mul_f32_e32 v6, v12, v6
	v_cndmask_b32_e32 v10, v25, v37, vcc
	v_cmp_gt_f32_e32 vcc, 0, v22
	v_sub_f32_e32 v10, v10, v14
	v_mul_f32_e32 v10, v12, v10
	v_cndmask_b32_e32 v20, v34, v38, vcc
	v_cmp_gt_f32_e32 vcc, 0, v23
	v_sub_f32_e32 v20, v20, v15
	v_mul_f32_e32 v20, v13, v20
	v_cndmask_b32_e32 v21, v35, v39, vcc
	v_sub_f32_e32 v21, v21, v15
	v_mul_f32_e32 v21, v13, v21
	ds_write_b32 v70, v3 offset:2992
	s_waitcnt vmcnt(0)
	v_fma_f32 v3, v8, v6, v4
	v_fma_f32 v6, v9, v10, v5
	v_fma_f32 v4, v8, v20, v4
	v_fmac_f32_e32 v5, v9, v21
	v_cvt_pk_bf16_f32 v3, v3, v4
	ds_write_b32 v70, v3 offset:3264
	v_cvt_pk_bf16_f32 v3, v6, v5
	global_load_dwordx2 v[8:9], v2, s[0:1] offset:56
	global_load_dwordx2 v[4:5], v2, s[4:5] offset:56
	v_lshlrev_b32_e32 v10, 16, v201
	v_and_b32_e32 v11, 0xffff0000, v201
	v_lshlrev_b32_e32 v6, 16, v205
	v_and_b32_e32 v7, 0xffff0000, v205
	v_and_b32_e32 v21, 0x7fffffff, v11
	v_and_b32_e32 v20, 0x7fffffff, v10
	v_and_b32_e32 v25, 0x7fffffff, v7
	v_and_b32_e32 v24, 0x7fffffff, v6
	v_pk_fma_f32 v[20:21], v[20:21], s[40:41], 1.0 op_sel_hi:[1,0,0]
	v_pk_fma_f32 v[24:25], v[24:25], s[40:41], 1.0 op_sel_hi:[1,0,0]
	v_rcp_f32_e32 v20, v20
	v_rcp_f32_e32 v21, v21
	v_rcp_f32_e32 v24, v24
	v_rcp_f32_e32 v25, v25
	v_pk_mul_f32 v[22:23], v[10:11], v[10:11]
	v_pk_mul_f32 v[34:35], v[6:7], v[6:7]
	v_pk_mul_f32 v[22:23], v[22:23], s[64:65] op_sel_hi:[1,0]
	v_pk_fma_f32 v[36:37], v[20:21], s[42:43], v[16:17] op_sel_hi:[1,0,0]
	v_pk_mul_f32 v[34:35], v[34:35], s[64:65] op_sel_hi:[1,0]
	v_exp_f32_e32 v22, v22
	v_exp_f32_e32 v23, v23
	v_pk_fma_f32 v[38:39], v[24:25], s[42:43], v[16:17] op_sel_hi:[1,0,0]
	v_pk_fma_f32 v[36:37], v[20:21], v[36:37], s[48:49] op_sel_hi:[1,1,0]
	v_exp_f32_e32 v34, v34
	v_exp_f32_e32 v35, v35
	v_pk_fma_f32 v[38:39], v[24:25], v[38:39], s[48:49] op_sel_hi:[1,1,0]
	v_pk_fma_f32 v[36:37], v[20:21], v[36:37], s[50:51] op_sel_hi:[1,1,0]
	v_pk_fma_f32 v[38:39], v[24:25], v[38:39], s[50:51] op_sel_hi:[1,1,0]
	v_pk_fma_f32 v[36:37], v[20:21], v[36:37], s[56:57] op_sel_hi:[1,1,0]
	v_pk_fma_f32 v[38:39], v[24:25], v[38:39], s[56:57] op_sel_hi:[1,1,0]
	v_pk_mul_f32 v[20:21], v[20:21], v[36:37]
	v_pk_mul_f32 v[24:25], v[24:25], v[38:39]
	v_pk_mul_f32 v[20:21], v[22:23], v[20:21]
	v_pk_mul_f32 v[22:23], v[34:35], v[24:25]
	v_pk_mul_f32 v[24:25], v[10:11], v[20:21]
	v_pk_fma_f32 v[20:21], v[10:11], v[20:21], v[10:11] neg_lo:[1,0,0] neg_hi:[1,0,0]
	v_cmp_gt_f32_e32 vcc, 0, v10
	v_pk_mul_f32 v[34:35], v[6:7], v[22:23]
	v_pk_fma_f32 v[22:23], v[6:7], v[22:23], v[6:7] neg_lo:[1,0,0] neg_hi:[1,0,0]
	v_cndmask_b32_e32 v10, v20, v24, vcc
	v_cmp_gt_f32_e32 vcc, 0, v11
	v_sub_f32_e32 v10, v10, v14
	v_mul_f32_e32 v10, v12, v10
	v_cndmask_b32_e32 v11, v21, v25, vcc
	v_cmp_gt_f32_e32 vcc, 0, v6
	v_sub_f32_e32 v11, v11, v14
	v_mul_f32_e32 v11, v12, v11
	v_cndmask_b32_e32 v6, v22, v34, vcc
	v_cmp_gt_f32_e32 vcc, 0, v7
	v_sub_f32_e32 v6, v6, v15
	v_mul_f32_e32 v6, v13, v6
	v_cndmask_b32_e32 v7, v23, v35, vcc
	v_sub_f32_e32 v7, v7, v15
	v_mul_f32_e32 v7, v13, v7
	ds_write_b32 v70, v3 offset:3536
	s_waitcnt vmcnt(0)
	v_fma_f32 v3, v8, v10, v4
	v_fma_f32 v10, v9, v11, v5
	v_fma_f32 v4, v8, v6, v4
	v_fmac_f32_e32 v5, v9, v7
	v_cvt_pk_bf16_f32 v3, v3, v4
	ds_write_b32 v70, v3 offset:3808
	v_cvt_pk_bf16_f32 v3, v10, v5
	global_load_dwordx2 v[22:23], v2, s[0:1] offset:64
	global_load_dwordx2 v[20:21], v2, s[4:5] offset:64
	ds_write_b32 v70, v3 offset:4080
	s_waitcnt vmcnt(3)
	v_lshlrev_b32_e32 v24, 16, v206
	v_and_b32_e32 v25, 0xffff0000, v206
	s_waitcnt vmcnt(2)
	v_lshlrev_b32_e32 v34, 16, v210
	v_and_b32_e32 v35, 0xffff0000, v210
	v_and_b32_e32 v37, 0x7fffffff, v25
	v_and_b32_e32 v36, 0x7fffffff, v24
	v_and_b32_e32 v41, 0x7fffffff, v35
	v_and_b32_e32 v40, 0x7fffffff, v34
	v_pk_fma_f32 v[36:37], v[36:37], s[40:41], 1.0 op_sel_hi:[1,0,0]
	v_pk_fma_f32 v[40:41], v[40:41], s[40:41], 1.0 op_sel_hi:[1,0,0]
	v_rcp_f32_e32 v36, v36
	v_rcp_f32_e32 v37, v37
	v_rcp_f32_e32 v40, v40
	v_rcp_f32_e32 v41, v41
	v_pk_mul_f32 v[38:39], v[24:25], v[24:25]
	v_pk_mul_f32 v[42:43], v[34:35], v[34:35]
	v_pk_mul_f32 v[38:39], v[38:39], s[64:65] op_sel_hi:[1,0]
	v_pk_fma_f32 v[44:45], v[36:37], s[42:43], v[16:17] op_sel_hi:[1,0,0]
	v_pk_mul_f32 v[42:43], v[42:43], s[64:65] op_sel_hi:[1,0]
	v_exp_f32_e32 v38, v38
	v_exp_f32_e32 v39, v39
	v_pk_fma_f32 v[46:47], v[40:41], s[42:43], v[16:17] op_sel_hi:[1,0,0]
	v_pk_fma_f32 v[44:45], v[36:37], v[44:45], s[48:49] op_sel_hi:[1,1,0]
	v_exp_f32_e32 v42, v42
	v_exp_f32_e32 v43, v43
	v_pk_fma_f32 v[46:47], v[40:41], v[46:47], s[48:49] op_sel_hi:[1,1,0]
	v_pk_fma_f32 v[44:45], v[36:37], v[44:45], s[50:51] op_sel_hi:[1,1,0]
	v_pk_fma_f32 v[46:47], v[40:41], v[46:47], s[50:51] op_sel_hi:[1,1,0]
	v_pk_fma_f32 v[44:45], v[36:37], v[44:45], s[56:57] op_sel_hi:[1,1,0]
	v_pk_fma_f32 v[46:47], v[40:41], v[46:47], s[56:57] op_sel_hi:[1,1,0]
	v_pk_mul_f32 v[36:37], v[36:37], v[44:45]
	v_pk_mul_f32 v[40:41], v[40:41], v[46:47]
	v_pk_mul_f32 v[36:37], v[38:39], v[36:37]
	v_pk_mul_f32 v[38:39], v[42:43], v[40:41]
	v_pk_mul_f32 v[40:41], v[24:25], v[36:37]
	v_pk_fma_f32 v[36:37], v[24:25], v[36:37], v[24:25] neg_lo:[1,0,0] neg_hi:[1,0,0]
	v_cmp_gt_f32_e32 vcc, 0, v24
	v_pk_mul_f32 v[42:43], v[34:35], v[38:39]
	v_pk_fma_f32 v[38:39], v[34:35], v[38:39], v[34:35] neg_lo:[1,0,0] neg_hi:[1,0,0]
	v_cndmask_b32_e32 v3, v36, v40, vcc
	v_cmp_gt_f32_e32 vcc, 0, v25
	v_sub_f32_e32 v3, v3, v14
	v_mul_f32_e32 v3, v12, v3
	v_cndmask_b32_e32 v4, v37, v41, vcc
	v_cmp_gt_f32_e32 vcc, 0, v34
	v_sub_f32_e32 v4, v4, v14
	v_mul_f32_e32 v4, v12, v4
	v_cndmask_b32_e32 v8, v38, v42, vcc
	v_cmp_gt_f32_e32 vcc, 0, v35
	v_sub_f32_e32 v8, v8, v15
	v_mul_f32_e32 v8, v13, v8
	v_cndmask_b32_e32 v24, v39, v43, vcc
	v_sub_f32_e32 v24, v24, v15
	v_mul_f32_e32 v24, v13, v24
	s_waitcnt vmcnt(0)
	v_fma_f32 v3, v22, v3, v20
	v_fma_f32 v4, v23, v4, v21
	v_fma_f32 v8, v22, v8, v20
	v_fmac_f32_e32 v21, v23, v24
	v_cvt_pk_bf16_f32 v3, v3, v8
	ds_write_b32 v70, v3 offset:4352
	v_cvt_pk_bf16_f32 v3, v4, v21
	global_load_dwordx2 v[22:23], v2, s[0:1] offset:72
	global_load_dwordx2 v[20:21], v2, s[4:5] offset:72
	v_lshlrev_b32_e32 v8, 16, v207
	v_and_b32_e32 v9, 0xffff0000, v207
	v_lshlrev_b32_e32 v4, 16, v211
	v_and_b32_e32 v5, 0xffff0000, v211
	v_and_b32_e32 v25, 0x7fffffff, v9
	v_and_b32_e32 v24, 0x7fffffff, v8
	v_and_b32_e32 v37, 0x7fffffff, v5
	v_and_b32_e32 v36, 0x7fffffff, v4
	v_pk_fma_f32 v[24:25], v[24:25], s[40:41], 1.0 op_sel_hi:[1,0,0]
	v_pk_fma_f32 v[36:37], v[36:37], s[40:41], 1.0 op_sel_hi:[1,0,0]
	v_rcp_f32_e32 v24, v24
	v_rcp_f32_e32 v25, v25
	v_rcp_f32_e32 v36, v36
	v_rcp_f32_e32 v37, v37
	v_pk_mul_f32 v[34:35], v[8:9], v[8:9]
	v_pk_mul_f32 v[38:39], v[4:5], v[4:5]
	v_pk_mul_f32 v[34:35], v[34:35], s[64:65] op_sel_hi:[1,0]
	v_pk_fma_f32 v[40:41], v[24:25], s[42:43], v[16:17] op_sel_hi:[1,0,0]
	v_pk_mul_f32 v[38:39], v[38:39], s[64:65] op_sel_hi:[1,0]
	v_exp_f32_e32 v34, v34
	v_exp_f32_e32 v35, v35
	v_pk_fma_f32 v[42:43], v[36:37], s[42:43], v[16:17] op_sel_hi:[1,0,0]
	v_pk_fma_f32 v[40:41], v[24:25], v[40:41], s[48:49] op_sel_hi:[1,1,0]
	v_exp_f32_e32 v38, v38
	v_exp_f32_e32 v39, v39
	v_pk_fma_f32 v[42:43], v[36:37], v[42:43], s[48:49] op_sel_hi:[1,1,0]
	v_pk_fma_f32 v[40:41], v[24:25], v[40:41], s[50:51] op_sel_hi:[1,1,0]
	v_pk_fma_f32 v[42:43], v[36:37], v[42:43], s[50:51] op_sel_hi:[1,1,0]
	v_pk_fma_f32 v[40:41], v[24:25], v[40:41], s[56:57] op_sel_hi:[1,1,0]
	v_pk_fma_f32 v[42:43], v[36:37], v[42:43], s[56:57] op_sel_hi:[1,1,0]
	v_pk_mul_f32 v[24:25], v[24:25], v[40:41]
	v_pk_mul_f32 v[36:37], v[36:37], v[42:43]
	v_pk_mul_f32 v[24:25], v[34:35], v[24:25]
	v_pk_mul_f32 v[34:35], v[38:39], v[36:37]
	v_pk_mul_f32 v[36:37], v[8:9], v[24:25]
	v_pk_fma_f32 v[24:25], v[8:9], v[24:25], v[8:9] neg_lo:[1,0,0] neg_hi:[1,0,0]
	v_cmp_gt_f32_e32 vcc, 0, v8
	v_pk_mul_f32 v[38:39], v[4:5], v[34:35]
	v_pk_fma_f32 v[34:35], v[4:5], v[34:35], v[4:5] neg_lo:[1,0,0] neg_hi:[1,0,0]
	v_cndmask_b32_e32 v8, v24, v36, vcc
	v_cmp_gt_f32_e32 vcc, 0, v9
	v_sub_f32_e32 v8, v8, v14
	v_mul_f32_e32 v8, v12, v8
	v_cndmask_b32_e32 v9, v25, v37, vcc
	v_cmp_gt_f32_e32 vcc, 0, v4
	v_sub_f32_e32 v9, v9, v14
	v_mul_f32_e32 v9, v12, v9
	v_cndmask_b32_e32 v4, v34, v38, vcc
	v_cmp_gt_f32_e32 vcc, 0, v5
	v_sub_f32_e32 v4, v4, v15
	v_mul_f32_e32 v4, v13, v4
	v_cndmask_b32_e32 v5, v35, v39, vcc
	v_sub_f32_e32 v5, v5, v15
	ds_write_b32 v70, v3 offset:4624
	v_mul_f32_e32 v5, v13, v5
	s_waitcnt vmcnt(0)
	v_fma_f32 v3, v22, v8, v20
	v_fma_f32 v8, v23, v9, v21
	v_fma_f32 v4, v22, v4, v20
	v_cvt_pk_bf16_f32 v3, v3, v4
	v_fmac_f32_e32 v21, v23, v5
	ds_write_b32 v70, v3 offset:4896
	v_cvt_pk_bf16_f32 v3, v8, v21
	global_load_dwordx2 v[8:9], v2, s[0:1] offset:80
	global_load_dwordx2 v[4:5], v2, s[4:5] offset:80
	v_lshlrev_b32_e32 v20, 16, v208
	v_and_b32_e32 v21, 0xffff0000, v208
	v_lshlrev_b32_e32 v22, 16, v212
	v_and_b32_e32 v23, 0xffff0000, v212
	v_and_b32_e32 v25, 0x7fffffff, v21
	v_and_b32_e32 v24, 0x7fffffff, v20
	v_and_b32_e32 v37, 0x7fffffff, v23
	v_and_b32_e32 v36, 0x7fffffff, v22
	v_pk_fma_f32 v[24:25], v[24:25], s[40:41], 1.0 op_sel_hi:[1,0,0]
	v_pk_fma_f32 v[36:37], v[36:37], s[40:41], 1.0 op_sel_hi:[1,0,0]
	v_rcp_f32_e32 v24, v24
	v_rcp_f32_e32 v25, v25
	v_rcp_f32_e32 v36, v36
	v_rcp_f32_e32 v37, v37
	v_pk_mul_f32 v[34:35], v[20:21], v[20:21]
	v_pk_mul_f32 v[38:39], v[22:23], v[22:23]
	v_pk_mul_f32 v[34:35], v[34:35], s[64:65] op_sel_hi:[1,0]
	v_pk_fma_f32 v[40:41], v[24:25], s[42:43], v[16:17] op_sel_hi:[1,0,0]
	v_pk_mul_f32 v[38:39], v[38:39], s[64:65] op_sel_hi:[1,0]
	v_exp_f32_e32 v34, v34
	v_exp_f32_e32 v35, v35
	v_pk_fma_f32 v[42:43], v[36:37], s[42:43], v[16:17] op_sel_hi:[1,0,0]
	v_pk_fma_f32 v[40:41], v[24:25], v[40:41], s[48:49] op_sel_hi:[1,1,0]
	v_exp_f32_e32 v38, v38
	v_exp_f32_e32 v39, v39
	v_pk_fma_f32 v[42:43], v[36:37], v[42:43], s[48:49] op_sel_hi:[1,1,0]
	v_pk_fma_f32 v[40:41], v[24:25], v[40:41], s[50:51] op_sel_hi:[1,1,0]
	v_pk_fma_f32 v[42:43], v[36:37], v[42:43], s[50:51] op_sel_hi:[1,1,0]
	v_pk_fma_f32 v[40:41], v[24:25], v[40:41], s[56:57] op_sel_hi:[1,1,0]
	v_pk_fma_f32 v[42:43], v[36:37], v[42:43], s[56:57] op_sel_hi:[1,1,0]
	v_pk_mul_f32 v[24:25], v[24:25], v[40:41]
	v_pk_mul_f32 v[36:37], v[36:37], v[42:43]
	v_pk_mul_f32 v[24:25], v[34:35], v[24:25]
	v_pk_mul_f32 v[34:35], v[38:39], v[36:37]
	v_pk_mul_f32 v[36:37], v[20:21], v[24:25]
	v_pk_fma_f32 v[24:25], v[20:21], v[24:25], v[20:21] neg_lo:[1,0,0] neg_hi:[1,0,0]
	v_cmp_gt_f32_e32 vcc, 0, v20
	v_pk_mul_f32 v[38:39], v[22:23], v[34:35]
	v_pk_fma_f32 v[34:35], v[22:23], v[34:35], v[22:23] neg_lo:[1,0,0] neg_hi:[1,0,0]
	v_cndmask_b32_e32 v6, v24, v36, vcc
	v_cmp_gt_f32_e32 vcc, 0, v21
	v_sub_f32_e32 v6, v6, v14
	v_mul_f32_e32 v6, v12, v6
	v_cndmask_b32_e32 v10, v25, v37, vcc
	v_cmp_gt_f32_e32 vcc, 0, v22
	v_sub_f32_e32 v10, v10, v14
	v_mul_f32_e32 v10, v12, v10
	v_cndmask_b32_e32 v20, v34, v38, vcc
	v_cmp_gt_f32_e32 vcc, 0, v23
	v_sub_f32_e32 v20, v20, v15
	v_mul_f32_e32 v20, v13, v20
	v_cndmask_b32_e32 v21, v35, v39, vcc
	v_sub_f32_e32 v21, v21, v15
	v_mul_f32_e32 v21, v13, v21
	ds_write_b32 v70, v3 offset:5168
	s_waitcnt vmcnt(0)
	v_fma_f32 v3, v8, v6, v4
	v_fma_f32 v6, v9, v10, v5
	v_fma_f32 v4, v8, v20, v4
	v_fmac_f32_e32 v5, v9, v21
	v_cvt_pk_bf16_f32 v3, v3, v4
	ds_write_b32 v70, v3 offset:5440
	v_cvt_pk_bf16_f32 v3, v6, v5
	global_load_dwordx2 v[8:9], v2, s[0:1] offset:88
	global_load_dwordx2 v[4:5], v2, s[4:5] offset:88
	v_lshlrev_b32_e32 v10, 16, v209
	v_and_b32_e32 v11, 0xffff0000, v209
	v_lshlrev_b32_e32 v6, 16, v213
	v_and_b32_e32 v7, 0xffff0000, v213
	v_and_b32_e32 v21, 0x7fffffff, v11
	v_and_b32_e32 v20, 0x7fffffff, v10
	v_and_b32_e32 v25, 0x7fffffff, v7
	v_and_b32_e32 v24, 0x7fffffff, v6
	v_pk_fma_f32 v[20:21], v[20:21], s[40:41], 1.0 op_sel_hi:[1,0,0]
	v_pk_fma_f32 v[24:25], v[24:25], s[40:41], 1.0 op_sel_hi:[1,0,0]
	v_rcp_f32_e32 v20, v20
	v_rcp_f32_e32 v21, v21
	v_rcp_f32_e32 v24, v24
	v_rcp_f32_e32 v25, v25
	v_pk_mul_f32 v[22:23], v[10:11], v[10:11]
	v_pk_mul_f32 v[34:35], v[6:7], v[6:7]
	v_pk_mul_f32 v[22:23], v[22:23], s[64:65] op_sel_hi:[1,0]
	v_pk_fma_f32 v[36:37], v[20:21], s[42:43], v[16:17] op_sel_hi:[1,0,0]
	v_pk_mul_f32 v[34:35], v[34:35], s[64:65] op_sel_hi:[1,0]
	v_exp_f32_e32 v22, v22
	v_exp_f32_e32 v23, v23
	v_pk_fma_f32 v[38:39], v[24:25], s[42:43], v[16:17] op_sel_hi:[1,0,0]
	v_pk_fma_f32 v[36:37], v[20:21], v[36:37], s[48:49] op_sel_hi:[1,1,0]
	v_exp_f32_e32 v34, v34
	v_exp_f32_e32 v35, v35
	v_pk_fma_f32 v[38:39], v[24:25], v[38:39], s[48:49] op_sel_hi:[1,1,0]
	v_pk_fma_f32 v[36:37], v[20:21], v[36:37], s[50:51] op_sel_hi:[1,1,0]
	v_pk_fma_f32 v[38:39], v[24:25], v[38:39], s[50:51] op_sel_hi:[1,1,0]
	v_pk_fma_f32 v[36:37], v[20:21], v[36:37], s[56:57] op_sel_hi:[1,1,0]
	v_pk_fma_f32 v[38:39], v[24:25], v[38:39], s[56:57] op_sel_hi:[1,1,0]
	v_pk_mul_f32 v[20:21], v[20:21], v[36:37]
	v_pk_mul_f32 v[24:25], v[24:25], v[38:39]
	v_pk_mul_f32 v[20:21], v[22:23], v[20:21]
	v_pk_mul_f32 v[22:23], v[34:35], v[24:25]
	v_pk_mul_f32 v[24:25], v[10:11], v[20:21]
	v_pk_fma_f32 v[20:21], v[10:11], v[20:21], v[10:11] neg_lo:[1,0,0] neg_hi:[1,0,0]
	v_cmp_gt_f32_e32 vcc, 0, v10
	v_pk_mul_f32 v[34:35], v[6:7], v[22:23]
	v_pk_fma_f32 v[22:23], v[6:7], v[22:23], v[6:7] neg_lo:[1,0,0] neg_hi:[1,0,0]
	v_cndmask_b32_e32 v10, v20, v24, vcc
	v_cmp_gt_f32_e32 vcc, 0, v11
	v_sub_f32_e32 v10, v10, v14
	v_mul_f32_e32 v10, v12, v10
	v_cndmask_b32_e32 v11, v21, v25, vcc
	v_cmp_gt_f32_e32 vcc, 0, v6
	v_sub_f32_e32 v11, v11, v14
	v_mul_f32_e32 v11, v12, v11
	v_cndmask_b32_e32 v6, v22, v34, vcc
	v_cmp_gt_f32_e32 vcc, 0, v7
	v_sub_f32_e32 v6, v6, v15
	v_mul_f32_e32 v6, v13, v6
	v_cndmask_b32_e32 v7, v23, v35, vcc
	v_sub_f32_e32 v7, v7, v15
	v_mul_f32_e32 v7, v13, v7
	ds_write_b32 v70, v3 offset:5712
	s_waitcnt vmcnt(0)
	v_fma_f32 v3, v8, v10, v4
	v_fma_f32 v10, v9, v11, v5
	v_fma_f32 v4, v8, v6, v4
	v_fmac_f32_e32 v5, v9, v7
	v_cvt_pk_bf16_f32 v3, v3, v4
	ds_write_b32 v70, v3 offset:5984
	v_cvt_pk_bf16_f32 v3, v10, v5
	global_load_dwordx2 v[20:21], v2, s[0:1] offset:96
	s_nop 0
	global_load_dwordx2 v[18:19], v2, s[4:5] offset:96
	ds_write_b32 v70, v3 offset:6256
	s_waitcnt vmcnt(3)
	v_lshlrev_b32_e32 v22, 16, v214
	v_and_b32_e32 v23, 0xffff0000, v214
	s_waitcnt vmcnt(2)
	v_lshlrev_b32_e32 v24, 16, v218
	v_and_b32_e32 v25, 0xffff0000, v218
	v_and_b32_e32 v35, 0x7fffffff, v23
	v_and_b32_e32 v34, 0x7fffffff, v22
	v_and_b32_e32 v39, 0x7fffffff, v25
	v_and_b32_e32 v38, 0x7fffffff, v24
	v_pk_fma_f32 v[34:35], v[34:35], s[40:41], 1.0 op_sel_hi:[1,0,0]
	v_pk_fma_f32 v[38:39], v[38:39], s[40:41], 1.0 op_sel_hi:[1,0,0]
	v_rcp_f32_e32 v34, v34
	v_rcp_f32_e32 v35, v35
	v_rcp_f32_e32 v38, v38
	v_rcp_f32_e32 v39, v39
	v_pk_mul_f32 v[36:37], v[22:23], v[22:23]
	v_pk_mul_f32 v[40:41], v[24:25], v[24:25]
	v_pk_mul_f32 v[36:37], v[36:37], s[64:65] op_sel_hi:[1,0]
	v_pk_fma_f32 v[42:43], v[34:35], s[42:43], v[16:17] op_sel_hi:[1,0,0]
	v_pk_mul_f32 v[40:41], v[40:41], s[64:65] op_sel_hi:[1,0]
	v_exp_f32_e32 v36, v36
	v_exp_f32_e32 v37, v37
	v_pk_fma_f32 v[44:45], v[38:39], s[42:43], v[16:17] op_sel_hi:[1,0,0]
	v_pk_fma_f32 v[42:43], v[34:35], v[42:43], s[48:49] op_sel_hi:[1,1,0]
	v_exp_f32_e32 v40, v40
	v_exp_f32_e32 v41, v41
	v_pk_fma_f32 v[44:45], v[38:39], v[44:45], s[48:49] op_sel_hi:[1,1,0]
	v_pk_fma_f32 v[42:43], v[34:35], v[42:43], s[50:51] op_sel_hi:[1,1,0]
	v_pk_fma_f32 v[44:45], v[38:39], v[44:45], s[50:51] op_sel_hi:[1,1,0]
	v_pk_fma_f32 v[42:43], v[34:35], v[42:43], s[56:57] op_sel_hi:[1,1,0]
	v_pk_fma_f32 v[44:45], v[38:39], v[44:45], s[56:57] op_sel_hi:[1,1,0]
	v_pk_mul_f32 v[34:35], v[34:35], v[42:43]
	v_pk_mul_f32 v[38:39], v[38:39], v[44:45]
	v_pk_mul_f32 v[34:35], v[36:37], v[34:35]
	v_pk_mul_f32 v[36:37], v[40:41], v[38:39]
	v_pk_mul_f32 v[38:39], v[22:23], v[34:35]
	v_pk_fma_f32 v[34:35], v[22:23], v[34:35], v[22:23] neg_lo:[1,0,0] neg_hi:[1,0,0]
	v_cmp_gt_f32_e32 vcc, 0, v22
	v_pk_mul_f32 v[40:41], v[24:25], v[36:37]
	v_pk_fma_f32 v[36:37], v[24:25], v[36:37], v[24:25] neg_lo:[1,0,0] neg_hi:[1,0,0]
	v_cndmask_b32_e32 v3, v34, v38, vcc
	v_cmp_gt_f32_e32 vcc, 0, v23
	v_sub_f32_e32 v3, v3, v14
	v_mul_f32_e32 v3, v12, v3
	v_cndmask_b32_e32 v4, v35, v39, vcc
	v_cmp_gt_f32_e32 vcc, 0, v24
	v_sub_f32_e32 v4, v4, v14
	v_mul_f32_e32 v4, v12, v4
	v_cndmask_b32_e32 v8, v36, v40, vcc
	v_cmp_gt_f32_e32 vcc, 0, v25
	v_sub_f32_e32 v8, v8, v15
	v_mul_f32_e32 v8, v13, v8
	v_cndmask_b32_e32 v22, v37, v41, vcc
	v_sub_f32_e32 v22, v22, v15
	v_mul_f32_e32 v22, v13, v22
	s_waitcnt vmcnt(0)
	v_fma_f32 v3, v20, v3, v18
	v_fma_f32 v4, v21, v4, v19
	v_fma_f32 v8, v20, v8, v18
	v_fmac_f32_e32 v19, v21, v22
	v_cvt_pk_bf16_f32 v3, v3, v8
	ds_write_b32 v70, v3 offset:6528
	v_cvt_pk_bf16_f32 v3, v4, v19
	global_load_dwordx2 v[20:21], v2, s[0:1] offset:104
	global_load_dwordx2 v[18:19], v2, s[4:5] offset:104
	v_lshlrev_b32_e32 v8, 16, v215
	v_and_b32_e32 v9, 0xffff0000, v215
	v_lshlrev_b32_e32 v4, 16, v219
	v_and_b32_e32 v5, 0xffff0000, v219
	v_and_b32_e32 v23, 0x7fffffff, v9
	v_and_b32_e32 v22, 0x7fffffff, v8
	v_and_b32_e32 v35, 0x7fffffff, v5
	v_and_b32_e32 v34, 0x7fffffff, v4
	v_pk_fma_f32 v[22:23], v[22:23], s[40:41], 1.0 op_sel_hi:[1,0,0]
	v_pk_fma_f32 v[34:35], v[34:35], s[40:41], 1.0 op_sel_hi:[1,0,0]
	v_rcp_f32_e32 v22, v22
	v_rcp_f32_e32 v23, v23
	v_rcp_f32_e32 v34, v34
	v_rcp_f32_e32 v35, v35
	v_pk_mul_f32 v[24:25], v[8:9], v[8:9]
	v_pk_mul_f32 v[36:37], v[4:5], v[4:5]
	v_pk_mul_f32 v[24:25], v[24:25], s[64:65] op_sel_hi:[1,0]
	v_pk_fma_f32 v[38:39], v[22:23], s[42:43], v[16:17] op_sel_hi:[1,0,0]
	v_pk_mul_f32 v[36:37], v[36:37], s[64:65] op_sel_hi:[1,0]
	v_exp_f32_e32 v24, v24
	v_exp_f32_e32 v25, v25
	v_pk_fma_f32 v[40:41], v[34:35], s[42:43], v[16:17] op_sel_hi:[1,0,0]
	v_pk_fma_f32 v[38:39], v[22:23], v[38:39], s[48:49] op_sel_hi:[1,1,0]
	v_exp_f32_e32 v36, v36
	v_exp_f32_e32 v37, v37
	v_pk_fma_f32 v[40:41], v[34:35], v[40:41], s[48:49] op_sel_hi:[1,1,0]
	v_pk_fma_f32 v[38:39], v[22:23], v[38:39], s[50:51] op_sel_hi:[1,1,0]
	v_pk_fma_f32 v[40:41], v[34:35], v[40:41], s[50:51] op_sel_hi:[1,1,0]
	v_pk_fma_f32 v[38:39], v[22:23], v[38:39], s[56:57] op_sel_hi:[1,1,0]
	v_pk_fma_f32 v[40:41], v[34:35], v[40:41], s[56:57] op_sel_hi:[1,1,0]
	v_pk_mul_f32 v[22:23], v[22:23], v[38:39]
	v_pk_mul_f32 v[34:35], v[34:35], v[40:41]
	v_pk_mul_f32 v[22:23], v[24:25], v[22:23]
	v_pk_mul_f32 v[24:25], v[36:37], v[34:35]
	v_pk_mul_f32 v[34:35], v[8:9], v[22:23]
	v_pk_fma_f32 v[22:23], v[8:9], v[22:23], v[8:9] neg_lo:[1,0,0] neg_hi:[1,0,0]
	v_cmp_gt_f32_e32 vcc, 0, v8
	v_pk_mul_f32 v[36:37], v[4:5], v[24:25]
	v_pk_fma_f32 v[24:25], v[4:5], v[24:25], v[4:5] neg_lo:[1,0,0] neg_hi:[1,0,0]
	v_cndmask_b32_e32 v8, v22, v34, vcc
	v_cmp_gt_f32_e32 vcc, 0, v9
	v_sub_f32_e32 v8, v8, v14
	v_mul_f32_e32 v8, v12, v8
	v_cndmask_b32_e32 v9, v23, v35, vcc
	v_cmp_gt_f32_e32 vcc, 0, v4
	v_sub_f32_e32 v9, v9, v14
	v_mul_f32_e32 v9, v12, v9
	v_cndmask_b32_e32 v4, v24, v36, vcc
	v_cmp_gt_f32_e32 vcc, 0, v5
	v_sub_f32_e32 v4, v4, v15
	v_mul_f32_e32 v4, v13, v4
	v_cndmask_b32_e32 v5, v25, v37, vcc
	v_sub_f32_e32 v5, v5, v15
	ds_write_b32 v70, v3 offset:6800
	v_mul_f32_e32 v5, v13, v5
	s_waitcnt vmcnt(0)
	v_fma_f32 v3, v20, v8, v18
	v_fma_f32 v8, v21, v9, v19
	v_fma_f32 v4, v20, v4, v18
	v_cvt_pk_bf16_f32 v3, v3, v4
	v_fmac_f32_e32 v19, v21, v5
	ds_write_b32 v70, v3 offset:7072
	v_cvt_pk_bf16_f32 v3, v8, v19
	global_load_dwordx2 v[8:9], v2, s[0:1] offset:112
	global_load_dwordx2 v[4:5], v2, s[4:5] offset:112
	v_lshlrev_b32_e32 v18, 16, v216
	v_and_b32_e32 v19, 0xffff0000, v216
	v_lshlrev_b32_e32 v20, 16, v220
	v_and_b32_e32 v21, 0xffff0000, v220
	v_and_b32_e32 v23, 0x7fffffff, v19
	v_and_b32_e32 v22, 0x7fffffff, v18
	v_and_b32_e32 v35, 0x7fffffff, v21
	v_and_b32_e32 v34, 0x7fffffff, v20
	v_pk_fma_f32 v[22:23], v[22:23], s[40:41], 1.0 op_sel_hi:[1,0,0]
	v_pk_fma_f32 v[34:35], v[34:35], s[40:41], 1.0 op_sel_hi:[1,0,0]
	v_rcp_f32_e32 v22, v22
	v_rcp_f32_e32 v23, v23
	v_rcp_f32_e32 v34, v34
	v_rcp_f32_e32 v35, v35
	v_pk_mul_f32 v[24:25], v[18:19], v[18:19]
	v_pk_mul_f32 v[36:37], v[20:21], v[20:21]
	v_pk_mul_f32 v[24:25], v[24:25], s[64:65] op_sel_hi:[1,0]
	v_pk_fma_f32 v[38:39], v[22:23], s[42:43], v[16:17] op_sel_hi:[1,0,0]
	v_pk_mul_f32 v[36:37], v[36:37], s[64:65] op_sel_hi:[1,0]
	v_exp_f32_e32 v24, v24
	v_exp_f32_e32 v25, v25
	v_pk_fma_f32 v[40:41], v[34:35], s[42:43], v[16:17] op_sel_hi:[1,0,0]
	v_pk_fma_f32 v[38:39], v[22:23], v[38:39], s[48:49] op_sel_hi:[1,1,0]
	v_exp_f32_e32 v36, v36
	v_exp_f32_e32 v37, v37
	v_pk_fma_f32 v[40:41], v[34:35], v[40:41], s[48:49] op_sel_hi:[1,1,0]
	v_pk_fma_f32 v[38:39], v[22:23], v[38:39], s[50:51] op_sel_hi:[1,1,0]
	v_pk_fma_f32 v[40:41], v[34:35], v[40:41], s[50:51] op_sel_hi:[1,1,0]
	v_pk_fma_f32 v[38:39], v[22:23], v[38:39], s[56:57] op_sel_hi:[1,1,0]
	v_pk_fma_f32 v[40:41], v[34:35], v[40:41], s[56:57] op_sel_hi:[1,1,0]
	v_pk_mul_f32 v[22:23], v[22:23], v[38:39]
	v_pk_mul_f32 v[34:35], v[34:35], v[40:41]
	v_pk_mul_f32 v[22:23], v[24:25], v[22:23]
	v_pk_mul_f32 v[24:25], v[36:37], v[34:35]
	v_pk_mul_f32 v[34:35], v[18:19], v[22:23]
	v_pk_fma_f32 v[22:23], v[18:19], v[22:23], v[18:19] neg_lo:[1,0,0] neg_hi:[1,0,0]
	v_cmp_gt_f32_e32 vcc, 0, v18
	v_pk_mul_f32 v[36:37], v[20:21], v[24:25]
	v_pk_fma_f32 v[24:25], v[20:21], v[24:25], v[20:21] neg_lo:[1,0,0] neg_hi:[1,0,0]
	v_cndmask_b32_e32 v6, v22, v34, vcc
	v_cmp_gt_f32_e32 vcc, 0, v19
	v_sub_f32_e32 v6, v6, v14
	v_mul_f32_e32 v6, v12, v6
	v_cndmask_b32_e32 v10, v23, v35, vcc
	v_cmp_gt_f32_e32 vcc, 0, v20
	v_sub_f32_e32 v10, v10, v14
	v_mul_f32_e32 v10, v12, v10
	v_cndmask_b32_e32 v18, v24, v36, vcc
	v_cmp_gt_f32_e32 vcc, 0, v21
	v_sub_f32_e32 v18, v18, v15
	v_mul_f32_e32 v18, v13, v18
	v_cndmask_b32_e32 v19, v25, v37, vcc
	v_sub_f32_e32 v19, v19, v15
	v_mul_f32_e32 v19, v13, v19
	ds_write_b32 v70, v3 offset:7344
	s_andn2_b64 vcc, exec, s[80:81]
	s_waitcnt vmcnt(0)
	v_fma_f32 v3, v8, v6, v4
	v_fma_f32 v6, v9, v10, v5
	v_fma_f32 v4, v8, v18, v4
	v_fmac_f32_e32 v5, v9, v19
	v_cvt_pk_bf16_f32 v3, v3, v4
	ds_write_b32 v70, v3 offset:7616
	v_cvt_pk_bf16_f32 v3, v6, v5
	global_load_dwordx2 v[8:9], v2, s[0:1] offset:120
	global_load_dwordx2 v[4:5], v2, s[4:5] offset:120
	v_lshlrev_b32_e32 v10, 16, v217
	v_and_b32_e32 v11, 0xffff0000, v217
	v_cndmask_b32_e64 v6, 0, 1, s[80:81]
	v_and_b32_e32 v19, 0x7fffffff, v11
	v_and_b32_e32 v18, 0x7fffffff, v10
	v_cmp_ne_u32_e64 s[4:5], 1, v6
	v_lshlrev_b32_e32 v6, 16, v221
	v_and_b32_e32 v7, 0xffff0000, v221
	v_pk_fma_f32 v[18:19], v[18:19], s[40:41], 1.0 op_sel_hi:[1,0,0]
	v_and_b32_e32 v23, 0x7fffffff, v7
	v_and_b32_e32 v22, 0x7fffffff, v6
	v_rcp_f32_e32 v18, v18
	v_rcp_f32_e32 v19, v19
	v_pk_fma_f32 v[22:23], v[22:23], s[40:41], 1.0 op_sel_hi:[1,0,0]
	v_pk_mul_f32 v[20:21], v[10:11], v[10:11]
	v_rcp_f32_e32 v22, v22
	v_rcp_f32_e32 v23, v23
	v_pk_mul_f32 v[20:21], v[20:21], s[64:65] op_sel_hi:[1,0]
	v_pk_fma_f32 v[34:35], v[18:19], s[42:43], v[16:17] op_sel_hi:[1,0,0]
	v_pk_mul_f32 v[24:25], v[6:7], v[6:7]
	v_exp_f32_e32 v20, v20
	v_exp_f32_e32 v21, v21
	v_pk_fma_f32 v[34:35], v[18:19], v[34:35], s[48:49] op_sel_hi:[1,1,0]
	v_pk_mul_f32 v[24:25], v[24:25], s[64:65] op_sel_hi:[1,0]
	v_pk_fma_f32 v[16:17], v[22:23], s[42:43], v[16:17] op_sel_hi:[1,0,0]
	v_pk_fma_f32 v[34:35], v[18:19], v[34:35], s[50:51] op_sel_hi:[1,1,0]
	v_exp_f32_e32 v24, v24
	v_exp_f32_e32 v25, v25
	v_pk_fma_f32 v[16:17], v[22:23], v[16:17], s[48:49] op_sel_hi:[1,1,0]
	v_pk_fma_f32 v[34:35], v[18:19], v[34:35], s[56:57] op_sel_hi:[1,1,0]
	v_pk_fma_f32 v[16:17], v[22:23], v[16:17], s[50:51] op_sel_hi:[1,1,0]
	v_pk_mul_f32 v[18:19], v[18:19], v[34:35]
	v_pk_fma_f32 v[16:17], v[22:23], v[16:17], s[56:57] op_sel_hi:[1,1,0]
	v_pk_mul_f32 v[18:19], v[20:21], v[18:19]
	v_pk_mul_f32 v[16:17], v[22:23], v[16:17]
	v_pk_mul_f32 v[20:21], v[10:11], v[18:19]
	v_pk_fma_f32 v[18:19], v[10:11], v[18:19], v[10:11] neg_lo:[1,0,0] neg_hi:[1,0,0]
	v_cmp_gt_f32_e64 s[0:1], 0, v10
	v_pk_mul_f32 v[16:17], v[24:25], v[16:17]
	ds_write_b32 v70, v3 offset:7888
	v_cndmask_b32_e64 v10, v18, v20, s[0:1]
	v_cmp_gt_f32_e64 s[0:1], 0, v11
	v_pk_mul_f32 v[22:23], v[6:7], v[16:17]
	v_pk_fma_f32 v[16:17], v[6:7], v[16:17], v[6:7] neg_lo:[1,0,0] neg_hi:[1,0,0]
	v_cndmask_b32_e64 v11, v19, v21, s[0:1]
	v_cmp_gt_f32_e64 s[0:1], 0, v6
	v_sub_f32_e32 v10, v10, v14
	v_sub_f32_e32 v11, v11, v14
	v_cndmask_b32_e64 v6, v16, v22, s[0:1]
	v_cmp_gt_f32_e64 s[0:1], 0, v7
	v_sub_f32_e32 v6, v6, v15
	v_mul_f32_e32 v10, v12, v10
	v_cndmask_b32_e64 v7, v17, v23, s[0:1]
	v_sub_f32_e32 v7, v7, v15
	v_mul_f32_e32 v11, v12, v11
	v_mul_f32_e32 v6, v13, v6
	v_mul_f32_e32 v7, v13, v7
	s_waitcnt vmcnt(0)
	v_fma_f32 v3, v8, v10, v4
	v_fma_f32 v10, v9, v11, v5
	v_fma_f32 v4, v8, v6, v4
	v_fmac_f32_e32 v5, v9, v7
	v_cvt_pk_bf16_f32 v3, v3, v4
	ds_write_b32 v70, v3 offset:8160
	v_cvt_pk_bf16_f32 v3, v10, v5
	v_lshl_add_u64 v[4:5], s[12:13], 0, v[28:29]
	ds_write_b32 v70, v3 offset:8432
	s_cbranch_vccnz .LBB0_458
	v_add_co_u32_e32 v6, vcc, 0x2688000, v4
	s_nop 1
	v_addc_co_u32_e32 v7, vcc, 0, v5, vcc
	global_load_dwordx4 v[6:9], v[6:7], off
	v_cndmask_b32_e64 v3, 0, 1, s[82:83]
	v_cmp_ne_u32_e64 s[6:7], 1, v3
	s_andn2_b64 vcc, exec, s[82:83]
	s_cbranch_vccz .LBB0_459
